# P6 epilogue: all 16 residual loads issued up front (counted vmcnt per block), row-sum atomics grouped at the end
# baseline (speedup 1.0000x reference)
;     __device__ __forceinline__ void operator()(f32x4 (&acc)[2][2][4][2], const Unit& u, int wr, int wc, int fr, int fq) const {
;         const int row0 = u.pm * BM + wr * 64 + fr, col0 = u.pn * BM + wc * 32 + 8 * fq;
; #pragma unroll
;         for (int ai = 0; ai < 2; ++ai)
; #pragma unroll
;             for (int m = 0; m < 4; ++m) {
;                 const int row = row0 + ai * HALF + m * 16;
;                 const size_t off = (size_t)row * DM + col0;
;                 float ss = 0.f;
; #pragma unroll
;                 for (int bj = 0; bj < 2; ++bj) {
;                     const u32x4 w = *(const u32x4*)(hb + off + bj * HALF);
;                     f32x4 h0, h1;
;                     h0[0] = __uint_as_float(w.x << 16); h0[1] = __uint_as_float(w.x & 0xffff0000u); h0[2] = __uint_as_float(w.y << 16); h0[3] = __uint_as_float(w.y & 0xffff0000u);
;                     h1[0] = __uint_as_float(w.z << 16); h1[1] = __uint_as_float(w.z & 0xffff0000u); h1[2] = __uint_as_float(w.w << 16); h1[3] = __uint_as_float(w.w & 0xffff0000u);
;                     h0 += acc[ai][bj][m][0]; h1 += acc[ai][bj][m][1];
;                     acc[ai][bj][m][0] = h0; acc[ai][bj][m][1] = h1;
;                     ss += ((h0[0] * h0[0] + h0[1] * h0[1]) + (h0[2] * h0[2] + h0[3] * h0[3])) + ((h1[0] * h1[0] + h1[1] * h1[1]) + (h1[2] * h1[2] + h1[3] * h1[3]));
;                 }
;                 ss += __shfl_xor(ss, 16); ss += __shfl_xor(ss, 32);
;                 if (fq == 0) __hip_atomic_fetch_add(hss + row, ss, __ATOMIC_RELAXED, __HIP_MEMORY_SCOPE_AGENT);
;             }
.LBB0_703:
	v_lshl_add_u32 v128, s28, 8, v182
	v_ashrrev_i32_e32 v129, 31, v128
	v_lshl_or_b32 v160, s30, 8, v186
	v_ashrrev_i32_e32 v161, 31, v160
	v_or_b32_e32 v130, 16, v128
	v_or_b32_e32 v132, 32, v128
	v_or_b32_e32 v134, 48, v128
	v_add_u32_e32 v136, 0x80, v128
	v_add_u32_e32 v138, 0x90, v128
	v_add_u32_e32 v140, 0xa0, v128
	v_add_u32_e32 v142, 0xb0, v128
	v_ashrrev_i32_e32 v131, 31, v130
	v_ashrrev_i32_e32 v133, 31, v132
	v_ashrrev_i32_e32 v135, 31, v134
	v_ashrrev_i32_e32 v137, 31, v136
	v_ashrrev_i32_e32 v139, 31, v138
	v_ashrrev_i32_e32 v141, 31, v140
	v_ashrrev_i32_e32 v143, 31, v142
	v_lshlrev_b64 v[244:245], 12, v[128:129]
	v_lshl_add_u64 v[244:245], s[38:39], 0, v[244:245]
	v_lshl_add_u64 v[244:245], v[160:161], 1, v[244:245]
	global_load_dwordx4 v[164:167], v[244:245], off
	global_load_dwordx4 v[168:171], v[244:245], off offset:256
	v_lshlrev_b64 v[246:247], 12, v[130:131]
	v_lshl_add_u64 v[246:247], s[38:39], 0, v[246:247]
	v_lshl_add_u64 v[246:247], v[160:161], 1, v[246:247]
	global_load_dwordx4 v[172:175], v[246:247], off
	global_load_dwordx4 v[176:179], v[246:247], off offset:256
	v_lshlrev_b64 v[244:245], 12, v[132:133]
	v_lshl_add_u64 v[244:245], s[38:39], 0, v[244:245]
	v_lshl_add_u64 v[244:245], v[160:161], 1, v[244:245]
	global_load_dwordx4 v[196:199], v[244:245], off
	global_load_dwordx4 v[200:203], v[244:245], off offset:256
	v_lshlrev_b64 v[246:247], 12, v[134:135]
	v_lshl_add_u64 v[246:247], s[38:39], 0, v[246:247]
	v_lshl_add_u64 v[246:247], v[160:161], 1, v[246:247]
	global_load_dwordx4 v[204:207], v[246:247], off
	global_load_dwordx4 v[208:211], v[246:247], off offset:256
	v_lshlrev_b64 v[244:245], 12, v[136:137]
	v_lshl_add_u64 v[244:245], s[38:39], 0, v[244:245]
	v_lshl_add_u64 v[244:245], v[160:161], 1, v[244:245]
	global_load_dwordx4 v[212:215], v[244:245], off
	global_load_dwordx4 v[216:219], v[244:245], off offset:256
	v_lshlrev_b64 v[246:247], 12, v[138:139]
	v_lshl_add_u64 v[246:247], s[38:39], 0, v[246:247]
	v_lshl_add_u64 v[246:247], v[160:161], 1, v[246:247]
	global_load_dwordx4 v[220:223], v[246:247], off
	global_load_dwordx4 v[224:227], v[246:247], off offset:256
	v_lshlrev_b64 v[244:245], 12, v[140:141]
	v_lshl_add_u64 v[244:245], s[38:39], 0, v[244:245]
	v_lshl_add_u64 v[244:245], v[160:161], 1, v[244:245]
	global_load_dwordx4 v[228:231], v[244:245], off
	global_load_dwordx4 v[232:235], v[244:245], off offset:256
	v_lshlrev_b64 v[246:247], 12, v[142:143]
	v_lshl_add_u64 v[246:247], s[38:39], 0, v[246:247]
	v_lshl_add_u64 v[246:247], v[160:161], 1, v[246:247]
	global_load_dwordx4 v[236:239], v[246:247], off
	global_load_dwordx4 v[240:243], v[246:247], off offset:256
	s_waitcnt vmcnt(14)
	v_lshlrev_b32_e32 v244, 16, v164
	v_and_b32_e32 v245, 0xffff0000, v164
	v_lshlrev_b32_e32 v164, 16, v165
	v_and_b32_e32 v165, 0xffff0000, v165
	v_lshlrev_b32_e32 v246, 16, v166
	v_and_b32_e32 v247, 0xffff0000, v166
	v_lshlrev_b32_e32 v166, 16, v167
	v_and_b32_e32 v167, 0xffff0000, v167
	v_lshlrev_b32_e32 v180, 16, v168
	v_and_b32_e32 v181, 0xffff0000, v168
	v_lshlrev_b32_e32 v168, 16, v169
	v_and_b32_e32 v169, 0xffff0000, v169
	v_lshlrev_b32_e32 v192, 16, v170
	v_and_b32_e32 v193, 0xffff0000, v170
	v_lshlrev_b32_e32 v170, 16, v171
	v_and_b32_e32 v171, 0xffff0000, v171
	v_pk_add_f32 v[42:43], v[42:43], v[164:165]
	v_pk_add_f32 v[40:41], v[40:41], v[244:245]
	v_pk_add_f32 v[38:39], v[38:39], v[166:167]
	v_pk_add_f32 v[36:37], v[36:37], v[246:247]
	v_pk_add_f32 v[46:47], v[46:47], v[168:169]
	v_pk_add_f32 v[44:45], v[44:45], v[180:181]
	v_pk_add_f32 v[54:55], v[54:55], v[170:171]
	v_pk_add_f32 v[52:53], v[52:53], v[192:193]
	v_mul_f32_e32 v164, v41, v41
	v_mul_f32_e32 v165, v43, v43
	v_mul_f32_e32 v166, v37, v37
	v_mul_f32_e32 v167, v39, v39
	v_mul_f32_e32 v168, v45, v45
	v_mul_f32_e32 v169, v47, v47
	v_mul_f32_e32 v170, v53, v53
	v_mul_f32_e32 v171, v55, v55
	v_fmac_f32_e32 v164, v40, v40
	v_fmac_f32_e32 v165, v42, v42
	v_fmac_f32_e32 v166, v36, v36
	v_fmac_f32_e32 v167, v38, v38
	v_fmac_f32_e32 v168, v44, v44
	v_fmac_f32_e32 v169, v46, v46
	v_fmac_f32_e32 v170, v52, v52
	v_fmac_f32_e32 v171, v54, v54
	v_add_f32_e32 v164, v164, v165
	v_add_f32_e32 v165, v166, v167
	v_add_f32_e32 v166, v168, v169
	v_add_f32_e32 v167, v170, v171
	v_add_f32_e32 v164, v164, v165
	v_add_f32_e32 v165, v166, v167
	v_add_f32_e32 v164, v164, v165
	ds_bpermute_b32 v165, v184, v164
	s_waitcnt lgkmcnt(0)
	v_add_f32_e32 v164, v164, v165
	ds_bpermute_b32 v165, v185, v164
	s_waitcnt lgkmcnt(0)
	v_add_f32_e32 v164, v164, v165
	s_waitcnt vmcnt(13)
	v_lshlrev_b32_e32 v244, 16, v172
	v_and_b32_e32 v245, 0xffff0000, v172
	v_lshlrev_b32_e32 v172, 16, v173
	v_and_b32_e32 v173, 0xffff0000, v173
	v_lshlrev_b32_e32 v246, 16, v174
	v_and_b32_e32 v247, 0xffff0000, v174
	v_lshlrev_b32_e32 v174, 16, v175
	v_and_b32_e32 v175, 0xffff0000, v175
	s_waitcnt vmcnt(12)
	v_lshlrev_b32_e32 v180, 16, v176
	v_and_b32_e32 v181, 0xffff0000, v176
	v_lshlrev_b32_e32 v176, 16, v177
	v_and_b32_e32 v177, 0xffff0000, v177
	v_lshlrev_b32_e32 v192, 16, v178
	v_and_b32_e32 v193, 0xffff0000, v178
	v_lshlrev_b32_e32 v178, 16, v179
	v_and_b32_e32 v179, 0xffff0000, v179
	v_pk_add_f32 v[70:71], v[70:71], v[172:173]
	v_pk_add_f32 v[68:69], v[68:69], v[244:245]
	v_pk_add_f32 v[66:67], v[66:67], v[174:175]
	v_pk_add_f32 v[64:65], v[64:65], v[246:247]
	v_pk_add_f32 v[74:75], v[74:75], v[176:177]
	v_pk_add_f32 v[72:73], v[72:73], v[180:181]
	v_pk_add_f32 v[78:79], v[78:79], v[178:179]
	v_pk_add_f32 v[76:77], v[76:77], v[192:193]
	v_mul_f32_e32 v172, v69, v69
	v_mul_f32_e32 v173, v71, v71
	v_mul_f32_e32 v174, v65, v65
	v_mul_f32_e32 v175, v67, v67
	v_mul_f32_e32 v176, v73, v73
	v_mul_f32_e32 v177, v75, v75
	v_mul_f32_e32 v178, v77, v77
	v_mul_f32_e32 v179, v79, v79
	v_fmac_f32_e32 v172, v68, v68
	v_fmac_f32_e32 v173, v70, v70
	v_fmac_f32_e32 v174, v64, v64
	v_fmac_f32_e32 v175, v66, v66
	v_fmac_f32_e32 v176, v72, v72
	v_fmac_f32_e32 v177, v74, v74
	v_fmac_f32_e32 v178, v76, v76
	v_fmac_f32_e32 v179, v78, v78
	v_add_f32_e32 v172, v172, v173
	v_add_f32_e32 v173, v174, v175
	v_add_f32_e32 v174, v176, v177
	v_add_f32_e32 v175, v178, v179
	v_add_f32_e32 v172, v172, v173
	v_add_f32_e32 v173, v174, v175
	v_add_f32_e32 v172, v172, v173
	ds_bpermute_b32 v173, v184, v172
	s_waitcnt lgkmcnt(0)
;     __device__ __forceinline__ void operator()(f32x4 (&acc)[2][2][4][2], const Unit& u, int wr, int wc, int fr, int fq) const {
;     ...
;                 for (int bj = 0; bj < 2; ++bj) {
;                     const u32x4 w = *(const u32x4*)(hb + off + bj * HALF);
;                     f32x4 h0, h1;
;                     h0[0] = __uint_as_float(w.x << 16); h0[1] = __uint_as_float(w.x & 0xffff0000u); h0[2] = __uint_as_float(w.y << 16); h0[3] = __uint_as_float(w.y & 0xffff0000u);
;                     h1[0] = __uint_as_float(w.z << 16); h1[1] = __uint_as_float(w.z & 0xffff0000u); h1[2] = __uint_as_float(w.w << 16); h1[3] = __uint_as_float(w.w & 0xffff0000u);
;                     h0 += acc[ai][bj][m][0]; h1 += acc[ai][bj][m][1];
;                     acc[ai][bj][m][0] = h0; acc[ai][bj][m][1] = h1;
;                     ss += ((h0[0] * h0[0] + h0[1] * h0[1]) + (h0[2] * h0[2] + h0[3] * h0[3])) + ((h1[0] * h1[0] + h1[1] * h1[1]) + (h1[2] * h1[2] + h1[3] * h1[3]));
;                 }
;                 ss += __shfl_xor(ss, 16); ss += __shfl_xor(ss, 32);
	v_add_f32_e32 v172, v172, v173
	ds_bpermute_b32 v173, v185, v172
	s_waitcnt lgkmcnt(0)
	v_add_f32_e32 v172, v172, v173
	s_waitcnt vmcnt(11)
	v_lshlrev_b32_e32 v244, 16, v196
	v_and_b32_e32 v245, 0xffff0000, v196
	v_lshlrev_b32_e32 v196, 16, v197
	v_and_b32_e32 v197, 0xffff0000, v197
	v_lshlrev_b32_e32 v246, 16, v198
	v_and_b32_e32 v247, 0xffff0000, v198
	v_lshlrev_b32_e32 v198, 16, v199
	v_and_b32_e32 v199, 0xffff0000, v199
	s_waitcnt vmcnt(10)
	v_lshlrev_b32_e32 v180, 16, v200
	v_and_b32_e32 v181, 0xffff0000, v200
	v_lshlrev_b32_e32 v200, 16, v201
	v_and_b32_e32 v201, 0xffff0000, v201
	v_lshlrev_b32_e32 v192, 16, v202
	v_and_b32_e32 v193, 0xffff0000, v202
	v_lshlrev_b32_e32 v202, 16, v203
	v_and_b32_e32 v203, 0xffff0000, v203
	v_pk_add_f32 v[102:103], v[102:103], v[196:197]
	v_pk_add_f32 v[100:101], v[100:101], v[244:245]
	v_pk_add_f32 v[98:99], v[98:99], v[198:199]
	v_pk_add_f32 v[96:97], v[96:97], v[246:247]
	v_pk_add_f32 v[106:107], v[106:107], v[200:201]
	v_pk_add_f32 v[104:105], v[104:105], v[180:181]
	v_pk_add_f32 v[110:111], v[110:111], v[202:203]
	v_pk_add_f32 v[108:109], v[108:109], v[192:193]
	v_mul_f32_e32 v196, v101, v101
	v_mul_f32_e32 v197, v103, v103
	v_mul_f32_e32 v198, v97, v97
	v_mul_f32_e32 v199, v99, v99
	v_mul_f32_e32 v200, v105, v105
	v_mul_f32_e32 v201, v107, v107
	v_mul_f32_e32 v202, v109, v109
	v_mul_f32_e32 v203, v111, v111
	v_fmac_f32_e32 v196, v100, v100
	v_fmac_f32_e32 v197, v102, v102
	v_fmac_f32_e32 v198, v96, v96
	v_fmac_f32_e32 v199, v98, v98
	v_fmac_f32_e32 v200, v104, v104
	v_fmac_f32_e32 v201, v106, v106
	v_fmac_f32_e32 v202, v108, v108
	v_fmac_f32_e32 v203, v110, v110
	v_add_f32_e32 v196, v196, v197
	v_add_f32_e32 v197, v198, v199
	v_add_f32_e32 v198, v200, v201
	v_add_f32_e32 v199, v202, v203
	v_add_f32_e32 v196, v196, v197
	v_add_f32_e32 v197, v198, v199
	v_add_f32_e32 v196, v196, v197
	ds_bpermute_b32 v197, v184, v196
	s_waitcnt lgkmcnt(0)
	v_add_f32_e32 v196, v196, v197
	ds_bpermute_b32 v197, v185, v196
	s_waitcnt lgkmcnt(0)
	v_add_f32_e32 v196, v196, v197
	s_waitcnt vmcnt(9)
	v_lshlrev_b32_e32 v244, 16, v204
	v_and_b32_e32 v245, 0xffff0000, v204
	v_lshlrev_b32_e32 v204, 16, v205
	v_and_b32_e32 v205, 0xffff0000, v205
	v_lshlrev_b32_e32 v246, 16, v206
	v_and_b32_e32 v247, 0xffff0000, v206
	v_lshlrev_b32_e32 v206, 16, v207
	v_and_b32_e32 v207, 0xffff0000, v207
	s_waitcnt vmcnt(8)
	v_lshlrev_b32_e32 v180, 16, v208
	v_and_b32_e32 v181, 0xffff0000, v208
	v_lshlrev_b32_e32 v208, 16, v209
	v_and_b32_e32 v209, 0xffff0000, v209
	v_lshlrev_b32_e32 v192, 16, v210
	v_and_b32_e32 v193, 0xffff0000, v210
	v_lshlrev_b32_e32 v210, 16, v211
	v_and_b32_e32 v211, 0xffff0000, v211
	v_pk_add_f32 v[126:127], v[126:127], v[204:205]
	v_pk_add_f32 v[124:125], v[124:125], v[244:245]
	v_pk_add_f32 v[122:123], v[122:123], v[206:207]
	v_pk_add_f32 v[120:121], v[120:121], v[246:247]
	v_pk_add_f32 v[118:119], v[118:119], v[208:209]
	v_pk_add_f32 v[116:117], v[116:117], v[180:181]
	v_pk_add_f32 v[114:115], v[114:115], v[210:211]
	v_pk_add_f32 v[112:113], v[112:113], v[192:193]
	v_mul_f32_e32 v204, v125, v125
	v_mul_f32_e32 v205, v127, v127
	v_mul_f32_e32 v206, v121, v121
	v_mul_f32_e32 v207, v123, v123
	v_mul_f32_e32 v208, v117, v117
	v_mul_f32_e32 v209, v119, v119
	v_mul_f32_e32 v210, v113, v113
	v_mul_f32_e32 v211, v115, v115
	v_fmac_f32_e32 v204, v124, v124
	v_fmac_f32_e32 v205, v126, v126
	v_fmac_f32_e32 v206, v120, v120
	v_fmac_f32_e32 v207, v122, v122
	v_fmac_f32_e32 v208, v116, v116
	v_fmac_f32_e32 v209, v118, v118
	v_fmac_f32_e32 v210, v112, v112
	v_fmac_f32_e32 v211, v114, v114
	v_add_f32_e32 v204, v204, v205
	v_add_f32_e32 v205, v206, v207
	v_add_f32_e32 v206, v208, v209
	v_add_f32_e32 v207, v210, v211
	v_add_f32_e32 v204, v204, v205
	v_add_f32_e32 v205, v206, v207
	v_add_f32_e32 v204, v204, v205
	ds_bpermute_b32 v205, v184, v204
	s_waitcnt lgkmcnt(0)
	v_add_f32_e32 v204, v204, v205
	ds_bpermute_b32 v205, v185, v204
	s_waitcnt lgkmcnt(0)
	v_add_f32_e32 v204, v204, v205
	s_waitcnt vmcnt(7)
	v_lshlrev_b32_e32 v244, 16, v212
	v_and_b32_e32 v245, 0xffff0000, v212
	v_lshlrev_b32_e32 v212, 16, v213
	v_and_b32_e32 v213, 0xffff0000, v213
	v_lshlrev_b32_e32 v246, 16, v214
	v_and_b32_e32 v247, 0xffff0000, v214
	v_lshlrev_b32_e32 v214, 16, v215
	v_and_b32_e32 v215, 0xffff0000, v215
	s_waitcnt vmcnt(6)
	v_lshlrev_b32_e32 v180, 16, v216
	v_and_b32_e32 v181, 0xffff0000, v216
	v_lshlrev_b32_e32 v216, 16, v217
	v_and_b32_e32 v217, 0xffff0000, v217
	v_lshlrev_b32_e32 v192, 16, v218
	v_and_b32_e32 v193, 0xffff0000, v218
	v_lshlrev_b32_e32 v218, 16, v219
	v_and_b32_e32 v219, 0xffff0000, v219
	v_pk_add_f32 v[94:95], v[94:95], v[212:213]
	v_pk_add_f32 v[92:93], v[92:93], v[244:245]
	v_pk_add_f32 v[90:91], v[90:91], v[214:215]
	v_pk_add_f32 v[88:89], v[88:89], v[246:247]
	v_pk_add_f32 v[86:87], v[86:87], v[216:217]
	v_pk_add_f32 v[84:85], v[84:85], v[180:181]
	v_pk_add_f32 v[82:83], v[82:83], v[218:219]
	v_pk_add_f32 v[80:81], v[80:81], v[192:193]
	v_mul_f32_e32 v212, v93, v93
	v_mul_f32_e32 v213, v95, v95
	v_mul_f32_e32 v214, v89, v89
	v_mul_f32_e32 v215, v91, v91
	v_mul_f32_e32 v244, v85, v85
	v_mul_f32_e32 v245, v87, v87
	v_mul_f32_e32 v216, v81, v81
	v_mul_f32_e32 v217, v83, v83
	v_fmac_f32_e32 v212, v92, v92
	v_fmac_f32_e32 v213, v94, v94
	v_fmac_f32_e32 v214, v88, v88
	v_fmac_f32_e32 v215, v90, v90
	v_fmac_f32_e32 v244, v84, v84
	v_fmac_f32_e32 v245, v86, v86
	v_fmac_f32_e32 v216, v80, v80
	v_fmac_f32_e32 v217, v82, v82
	v_add_f32_e32 v212, v212, v213
	v_add_f32_e32 v213, v214, v215
	v_add_f32_e32 v214, v244, v245
	v_add_f32_e32 v215, v216, v217
	v_add_f32_e32 v212, v212, v213
	v_add_f32_e32 v213, v214, v215
	v_add_f32_e32 v212, v212, v213
	ds_bpermute_b32 v213, v184, v212
	s_waitcnt lgkmcnt(0)
;     __device__ __forceinline__ void operator()(f32x4 (&acc)[2][2][4][2], const Unit& u, int wr, int wc, int fr, int fq) const {
;     ...
;                 for (int bj = 0; bj < 2; ++bj) {
;                     const u32x4 w = *(const u32x4*)(hb + off + bj * HALF);
;                     f32x4 h0, h1;
;                     h0[0] = __uint_as_float(w.x << 16); h0[1] = __uint_as_float(w.x & 0xffff0000u); h0[2] = __uint_as_float(w.y << 16); h0[3] = __uint_as_float(w.y & 0xffff0000u);
;                     h1[0] = __uint_as_float(w.z << 16); h1[1] = __uint_as_float(w.z & 0xffff0000u); h1[2] = __uint_as_float(w.w << 16); h1[3] = __uint_as_float(w.w & 0xffff0000u);
;                     h0 += acc[ai][bj][m][0]; h1 += acc[ai][bj][m][1];
;                     acc[ai][bj][m][0] = h0; acc[ai][bj][m][1] = h1;
;                     ss += ((h0[0] * h0[0] + h0[1] * h0[1]) + (h0[2] * h0[2] + h0[3] * h0[3])) + ((h1[0] * h1[0] + h1[1] * h1[1]) + (h1[2] * h1[2] + h1[3] * h1[3]));
;                 }
;                 ss += __shfl_xor(ss, 16); ss += __shfl_xor(ss, 32);
;                 if (fq == 0) __hip_atomic_fetch_add(hss + row, ss, __ATOMIC_RELAXED, __HIP_MEMORY_SCOPE_AGENT);
	v_add_f32_e32 v212, v212, v213
	ds_bpermute_b32 v213, v185, v212
	s_waitcnt lgkmcnt(0)
	v_add_f32_e32 v212, v212, v213
	s_waitcnt vmcnt(5)
	v_lshlrev_b32_e32 v244, 16, v220
	v_and_b32_e32 v245, 0xffff0000, v220
	v_lshlrev_b32_e32 v220, 16, v221
	v_and_b32_e32 v221, 0xffff0000, v221
	v_lshlrev_b32_e32 v246, 16, v222
	v_and_b32_e32 v247, 0xffff0000, v222
	v_lshlrev_b32_e32 v222, 16, v223
	v_and_b32_e32 v223, 0xffff0000, v223
	s_waitcnt vmcnt(4)
	v_lshlrev_b32_e32 v180, 16, v224
	v_and_b32_e32 v181, 0xffff0000, v224
	v_lshlrev_b32_e32 v224, 16, v225
	v_and_b32_e32 v225, 0xffff0000, v225
	v_lshlrev_b32_e32 v192, 16, v226
	v_and_b32_e32 v193, 0xffff0000, v226
	v_lshlrev_b32_e32 v226, 16, v227
	v_and_b32_e32 v227, 0xffff0000, v227
	v_pk_add_f32 v[62:63], v[62:63], v[220:221]
	v_pk_add_f32 v[60:61], v[60:61], v[244:245]
	v_pk_add_f32 v[58:59], v[58:59], v[222:223]
	v_pk_add_f32 v[56:57], v[56:57], v[246:247]
	v_pk_add_f32 v[50:51], v[50:51], v[224:225]
	v_pk_add_f32 v[48:49], v[48:49], v[180:181]
	v_pk_add_f32 v[34:35], v[34:35], v[226:227]
	v_pk_add_f32 v[32:33], v[32:33], v[192:193]
	v_mul_f32_e32 v220, v61, v61
	v_mul_f32_e32 v221, v63, v63
	v_mul_f32_e32 v222, v57, v57
	v_mul_f32_e32 v223, v59, v59
	v_mul_f32_e32 v224, v49, v49
	v_mul_f32_e32 v225, v51, v51
	v_mul_f32_e32 v226, v33, v33
	v_mul_f32_e32 v227, v35, v35
	v_fmac_f32_e32 v220, v60, v60
	v_fmac_f32_e32 v221, v62, v62
	v_fmac_f32_e32 v222, v56, v56
	v_fmac_f32_e32 v223, v58, v58
	v_fmac_f32_e32 v224, v48, v48
	v_fmac_f32_e32 v225, v50, v50
	v_fmac_f32_e32 v226, v32, v32
	v_fmac_f32_e32 v227, v34, v34
	v_add_f32_e32 v220, v220, v221
	v_add_f32_e32 v221, v222, v223
	v_add_f32_e32 v222, v224, v225
	v_add_f32_e32 v223, v226, v227
	v_add_f32_e32 v220, v220, v221
	v_add_f32_e32 v221, v222, v223
	v_add_f32_e32 v220, v220, v221
	ds_bpermute_b32 v221, v184, v220
	s_waitcnt lgkmcnt(0)
	v_add_f32_e32 v220, v220, v221
	ds_bpermute_b32 v221, v185, v220
	s_waitcnt lgkmcnt(0)
	v_add_f32_e32 v220, v220, v221
	s_waitcnt vmcnt(3)
	v_lshlrev_b32_e32 v244, 16, v228
	v_and_b32_e32 v245, 0xffff0000, v228
	v_lshlrev_b32_e32 v228, 16, v229
	v_and_b32_e32 v229, 0xffff0000, v229
	v_lshlrev_b32_e32 v246, 16, v230
	v_and_b32_e32 v247, 0xffff0000, v230
	v_lshlrev_b32_e32 v230, 16, v231
	v_and_b32_e32 v231, 0xffff0000, v231
	s_waitcnt vmcnt(2)
	v_lshlrev_b32_e32 v180, 16, v232
	v_and_b32_e32 v181, 0xffff0000, v232
	v_lshlrev_b32_e32 v232, 16, v233
	v_and_b32_e32 v233, 0xffff0000, v233
	v_lshlrev_b32_e32 v192, 16, v234
	v_and_b32_e32 v193, 0xffff0000, v234
	v_lshlrev_b32_e32 v234, 16, v235
	v_and_b32_e32 v235, 0xffff0000, v235
	v_pk_add_f32 v[30:31], v[30:31], v[228:229]
	v_pk_add_f32 v[28:29], v[28:29], v[244:245]
	v_pk_add_f32 v[26:27], v[26:27], v[230:231]
	v_pk_add_f32 v[24:25], v[24:25], v[246:247]
	v_pk_add_f32 v[22:23], v[22:23], v[232:233]
	v_pk_add_f32 v[20:21], v[20:21], v[180:181]
	v_pk_add_f32 v[18:19], v[18:19], v[234:235]
	v_pk_add_f32 v[16:17], v[16:17], v[192:193]
	v_mul_f32_e32 v244, v29, v29
	v_mul_f32_e32 v245, v31, v31
	v_mul_f32_e32 v228, v25, v25
	v_mul_f32_e32 v229, v27, v27
	v_mul_f32_e32 v230, v21, v21
	v_mul_f32_e32 v231, v23, v23
	v_mul_f32_e32 v232, v17, v17
	v_mul_f32_e32 v233, v19, v19
	v_fmac_f32_e32 v244, v28, v28
	v_fmac_f32_e32 v245, v30, v30
	v_fmac_f32_e32 v228, v24, v24
	v_fmac_f32_e32 v229, v26, v26
	v_fmac_f32_e32 v230, v20, v20
	v_fmac_f32_e32 v231, v22, v22
	v_fmac_f32_e32 v232, v16, v16
	v_fmac_f32_e32 v233, v18, v18
	v_add_f32_e32 v244, v244, v245
	v_add_f32_e32 v245, v228, v229
	v_add_f32_e32 v228, v230, v231
	v_add_f32_e32 v229, v232, v233
	v_add_f32_e32 v244, v244, v245
	v_add_f32_e32 v245, v228, v229
	v_add_f32_e32 v244, v244, v245
	ds_bpermute_b32 v245, v184, v244
	s_waitcnt lgkmcnt(0)
	v_add_f32_e32 v244, v244, v245
	ds_bpermute_b32 v245, v185, v244
	s_waitcnt lgkmcnt(0)
	v_add_f32_e32 v228, v244, v245
	s_waitcnt vmcnt(1)
	v_lshlrev_b32_e32 v244, 16, v236
	v_and_b32_e32 v245, 0xffff0000, v236
	v_lshlrev_b32_e32 v236, 16, v237
	v_and_b32_e32 v237, 0xffff0000, v237
	v_lshlrev_b32_e32 v246, 16, v238
	v_and_b32_e32 v247, 0xffff0000, v238
	v_lshlrev_b32_e32 v238, 16, v239
	v_and_b32_e32 v239, 0xffff0000, v239
	s_waitcnt vmcnt(0)
	v_lshlrev_b32_e32 v180, 16, v240
	v_and_b32_e32 v181, 0xffff0000, v240
	v_lshlrev_b32_e32 v240, 16, v241
	v_and_b32_e32 v241, 0xffff0000, v241
	v_lshlrev_b32_e32 v192, 16, v242
	v_and_b32_e32 v193, 0xffff0000, v242
	v_lshlrev_b32_e32 v242, 16, v243
	v_and_b32_e32 v243, 0xffff0000, v243
	v_pk_add_f32 v[14:15], v[14:15], v[236:237]
	v_pk_add_f32 v[12:13], v[12:13], v[244:245]
	v_pk_add_f32 v[10:11], v[10:11], v[238:239]
	v_pk_add_f32 v[8:9], v[8:9], v[246:247]
	v_pk_add_f32 v[6:7], v[6:7], v[240:241]
	v_pk_add_f32 v[4:5], v[4:5], v[180:181]
	v_pk_add_f32 v[2:3], v[2:3], v[242:243]
	v_pk_add_f32 v[0:1], v[0:1], v[192:193]
	v_mul_f32_e32 v236, v13, v13
	v_mul_f32_e32 v237, v15, v15
	v_mul_f32_e32 v238, v9, v9
	v_mul_f32_e32 v239, v11, v11
	v_mul_f32_e32 v240, v5, v5
	v_mul_f32_e32 v241, v7, v7
	v_mul_f32_e32 v242, v1, v1
	v_mul_f32_e32 v243, v3, v3
	v_fmac_f32_e32 v236, v12, v12
	v_fmac_f32_e32 v237, v14, v14
	v_fmac_f32_e32 v238, v8, v8
	v_fmac_f32_e32 v239, v10, v10
	v_fmac_f32_e32 v240, v4, v4
	v_fmac_f32_e32 v241, v6, v6
	v_fmac_f32_e32 v242, v0, v0
	v_fmac_f32_e32 v243, v2, v2
	v_add_f32_e32 v236, v236, v237
	v_add_f32_e32 v237, v238, v239
	v_add_f32_e32 v238, v240, v241
	v_add_f32_e32 v239, v242, v243
	v_add_f32_e32 v236, v236, v237
	v_add_f32_e32 v237, v238, v239
	v_add_f32_e32 v236, v236, v237
	ds_bpermute_b32 v237, v184, v236
	s_waitcnt lgkmcnt(0)
	v_add_f32_e32 v236, v236, v237
	ds_bpermute_b32 v237, v185, v236
	s_waitcnt lgkmcnt(0)
	v_add_f32_e32 v236, v236, v237
	v_lshl_add_u64 v[162:163], v[128:129], 2, s[16:17]
	s_and_saveexec_b64 s[30:31], s[0:1]
	global_atomic_add_f32 v[162:163], v164, off
	global_atomic_add_f32 v[162:163], v172, off offset:64
	global_atomic_add_f32 v[162:163], v196, off offset:128
	global_atomic_add_f32 v[162:163], v204, off offset:192
	global_atomic_add_f32 v[162:163], v212, off offset:512
	global_atomic_add_f32 v[162:163], v220, off offset:576
	global_atomic_add_f32 v[162:163], v228, off offset:640
	global_atomic_add_f32 v[162:163], v236, off offset:704
	s_or_b64 exec, exec, s[30:31]
